# MLA loop: K/Kr/V LDS-DMA addressed via scalar base + 32-bit lane offset, removing the 64-bit vector address arithmetic from the loop
# speedup vs baseline: 1.0084x; 1.0084x over previous
; #define SBAR() __builtin_amdgcn_sched_barrier(0)
; #define LFIN() do { auto rr = __builtin_amdgcn_permlane32_swap(__float_as_uint(ps), __float_as_uint(ps), false, false); \
;     ps = __uint_as_float(rr[0]) + __uint_as_float(rr[1]); l_reg = l_reg * alpha + ps; } while (0)
; template <bool MLA>
; __device__ __forceinline__ void qkt_fin(f32x16& n0, f32x16& n1, const char* Ks, const char* Krs, const bf16x8* qr, int r32, int hi, const f32x16& cinit,
;                                         f32x16& p1, float alpha, float& l_reg, float ps0, bf16x8& pa2, bf16x8& pa3) {
;     ...
;     for (int s_ = 0; s_ < NSTEP; ++s_) {
;         const bool rope = s_ >= 8; const int d0 = rope ? s_ - 8 : s_; const int cb = (d0 * 16 + hi * 8) * 2;
;         const bf16x8 b0 = rope ? *reinterpret_cast<const bf16x8*>(Krs + KRSWZ(r32, cb)) : *reinterpret_cast<const bf16x8*>(Ks + KSWZ(r32, cb));
;         const bf16x8 b1 = rope ? *reinterpret_cast<const bf16x8*>(Krs + KRSWZ(32 + r32, cb)) : *reinterpret_cast<const bf16x8*>(Ks + KSWZ(32 + r32, cb));
;         if (s_ == 0) { n0 = __builtin_amdgcn_mfma_f32_32x32x16_bf16(b0, qr[0], cinit, 0, 0, 0); n1 = __builtin_amdgcn_mfma_f32_32x32x16_bf16(b1, qr[0], cinit, 0, 0, 0); }
;         else { n0 = __builtin_amdgcn_mfma_f32_32x32x16_bf16(b0, qr[s_], n0, 0, 0, 0); n1 = __builtin_amdgcn_mfma_f32_32x32x16_bf16(b1, qr[s_], n1, 0, 0, 0); }
;         if (s_ < 8) { p1[2 * s_] = __builtin_amdgcn_exp2f(p1[2 * s_]); p1[2 * s_ + 1] = __builtin_amdgcn_exp2f(p1[2 * s_ + 1]); ps += p1[2 * s_] + p1[2 * s_ + 1]; }
;         if (s_ == 4) PK4(p1, 0, pa2);
;         if (MLA && s_ == 8) { LFIN(); PK4(p1, 8, pa3); }
;         SBAR();
.LBB0_465:
	s_cmpk_lt_u32 s14, 0xfd
	s_waitcnt vmcnt(5) lgkmcnt(0)
	s_barrier
	s_cselect_b64 s[6:7], -1, 0
	s_cmpk_gt_u32 s14, 0xfc
	s_cselect_b64 s[8:9], -1, 0
	s_and_b64 vcc, exec, s[8:9]
	s_cbranch_vccnz .LBB0_467
	s_add_u32 s24, s84, 0x1ef00000
	s_addc_u32 s25, s85, 0
	s_add_i32 s10, s10, s19
	s_mov_b32 m0, s10
	s_nop 0
	global_load_lds_dwordx4 v196, s[24:25]
	s_add_u32 s24, s84, 0x1ef20000
	s_addc_u32 s25, s85, 0
	s_add_i32 m0, s10, 0x2000
	s_add_i32 s10, s20, s11
	global_load_lds_dwordx4 v196, s[24:25]
	s_add_u32 s24, s84, 0x908000
	s_addc_u32 s25, s85, 0
	s_add_i32 m0, s10, 0xc000
	s_nop 0
	global_load_lds_dwordx4 v194, s[24:25]
.LBB0_467:
	s_add_u32 s10, s84, 0x1eec0100
	s_addc_u32 s11, s85, 0
	s_add_i32 s21, s12, s21
	s_mov_b32 m0, s21
	s_nop 0
	global_load_lds_dwordx4 v198, s[10:11]
	s_add_u32 s10, s84, 0x1eee0100
	s_addc_u32 s11, s85, 0
	s_add_i32 m0, s21, 0x2000
	s_nop 0
	global_load_lds_dwordx4 v198, s[10:11]
	s_lshl_b32 s21, s13, 14
	s_add_i32 s24, s21, 0
	v_add_u32_e32 v85, s24, v224
	ds_read_b128 v[80:83], v85
	ds_read_b128 v[246:249], v85 offset:8192
	v_exp_f32_e32 v206, v96
	v_exp_f32_e32 v207, v97
	s_lshl_b32 s25, s13, 13
	s_waitcnt lgkmcnt(0)
	v_mfma_f32_32x32x16_bf16 v[112:127], v[80:83], v[172:175], v[64:79]
	s_sub_i32 s10, s24, s25
	v_add_f32_e32 v80, v207, v206
	v_add_f32_e32 v96, v80, v84
	v_mfma_f32_32x32x16_bf16 v[80:95], v[246:249], v[172:175], v[64:79]
	v_add_u32_e32 v97, s24, v225
	ds_read_b128 v[246:249], v97
	ds_read_b128 v[188:191], v97 offset:8192
	v_exp_f32_e32 v208, v98
	v_exp_f32_e32 v209, v99
	s_waitcnt lgkmcnt(0)
	v_mfma_f32_32x32x16_bf16 v[112:127], v[246:249], v[168:171], v[112:127]
	v_add_f32_e32 v97, v209, v208
	v_add_f32_e32 v243, v97, v96
	v_mfma_f32_32x32x16_bf16 v[80:95], v[188:191], v[168:171], v[80:95]
	v_add_u32_e32 v188, s24, v226
	ds_read_b128 v[96:99], v188
	ds_read_b128 v[188:191], v188 offset:8192
	v_exp_f32_e32 v245, v100
	v_exp_f32_e32 v246, v101
	s_waitcnt lgkmcnt(0)
	v_mfma_f32_32x32x16_bf16 v[112:127], v[96:99], v[164:167], v[112:127]
	v_add_f32_e32 v96, v246, v245
	v_add_f32_e32 v100, v96, v243
	v_mfma_f32_32x32x16_bf16 v[80:95], v[188:191], v[164:167], v[80:95]
	v_add_u32_e32 v101, s24, v227
	ds_read_b128 v[96:99], v101
	ds_read_b128 v[188:191], v101 offset:8192
	v_exp_f32_e32 v243, v102
	v_exp_f32_e32 v247, v103
	s_waitcnt lgkmcnt(0)
	v_mfma_f32_32x32x16_bf16 v[112:127], v[96:99], v[160:163], v[112:127]
	v_add_f32_e32 v96, v247, v243
	v_add_f32_e32 v248, v96, v100
	v_mfma_f32_32x32x16_bf16 v[80:95], v[188:191], v[160:163], v[80:95]
	v_add_u32_e32 v100, s24, v224
	ds_read_b128 v[96:99], v100 offset:128
	ds_read_b128 v[100:103], v100 offset:8320
	v_exp_f32_e32 v249, v104
	v_exp_f32_e32 v186, v105
	s_waitcnt lgkmcnt(0)
	v_mfma_f32_32x32x16_bf16 v[112:127], v[96:99], v[156:159], v[112:127]
	v_add_f32_e32 v96, v186, v249
	v_add_f32_e32 v104, v96, v248
	v_cvt_pk_bf16_f32 v96, v206, v207
	v_cvt_pk_bf16_f32 v97, v208, v209
	v_cvt_pk_bf16_f32 v98, v245, v246
	v_cvt_pk_bf16_f32 v99, v243, v247
	v_mfma_f32_32x32x16_bf16 v[80:95], v[100:103], v[156:159], v[80:95]
	v_permlane32_swap_b32_e32 v96, v98
	v_permlane32_swap_b32_e32 v97, v99
	v_add_u32_e32 v105, s24, v225
	ds_read_b128 v[100:103], v105 offset:128
	ds_read_b128 v[188:191], v105 offset:8320
	v_exp_f32_e32 v206, v106
	v_exp_f32_e32 v207, v107
	s_waitcnt lgkmcnt(0)
	v_mfma_f32_32x32x16_bf16 v[112:127], v[100:103], v[152:155], v[112:127]
	v_add_f32_e32 v100, v207, v206
	v_add_f32_e32 v208, v100, v104
	v_mfma_f32_32x32x16_bf16 v[80:95], v[188:191], v[152:155], v[80:95]
	v_add_u32_e32 v104, s24, v226
	ds_read_b128 v[100:103], v104 offset:128
	ds_read_b128 v[104:107], v104 offset:8320
	v_exp_f32_e32 v188, v108
	v_exp_f32_e32 v189, v109
	s_waitcnt lgkmcnt(0)
	v_mfma_f32_32x32x16_bf16 v[112:127], v[100:103], v[148:151], v[112:127]
	v_add_f32_e32 v100, v189, v188
	v_add_f32_e32 v108, v100, v208
	v_mfma_f32_32x32x16_bf16 v[80:95], v[104:107], v[148:151], v[80:95]
	v_add_u32_e32 v104, s24, v227
	ds_read_b128 v[100:103], v104 offset:128
	ds_read_b128 v[104:107], v104 offset:8320
	v_exp_f32_e32 v110, v110
	v_exp_f32_e32 v111, v111
	s_waitcnt lgkmcnt(0)
	v_mfma_f32_32x32x16_bf16 v[112:127], v[100:103], v[144:147], v[112:127]
	v_add_f32_e32 v100, v111, v110
	v_add_f32_e32 v100, v100, v108
	v_mfma_f32_32x32x16_bf16 v[80:95], v[104:107], v[144:147], v[80:95]
	v_add_u32_e32 v101, s10, v232
	ds_read_b128 v[102:105], v101 offset:49152
	v_add_u32_e32 v101, s10, v232
	ds_read_b128 v[106:109], v101 offset:53248
	v_mov_b32_e32 v101, v100
	s_nop 1
	v_permlane32_swap_b32_e32 v100, v101
	s_waitcnt lgkmcnt(0)
; #define SBAR() __builtin_amdgcn_sched_barrier(0)
; template <bool MLA>
; __device__ __forceinline__ void qkt_fin(f32x16& n0, f32x16& n1, const char* Ks, const char* Krs, const bf16x8* qr, int r32, int hi, const f32x16& cinit,
;                                         f32x16& p1, float alpha, float& l_reg, float ps0, bf16x8& pa2, bf16x8& pa3) {
;     ...
;     for (int s_ = 0; s_ < NSTEP; ++s_) {
;         const bool rope = s_ >= 8; const int d0 = rope ? s_ - 8 : s_; const int cb = (d0 * 16 + hi * 8) * 2;
;         const bf16x8 b0 = rope ? *reinterpret_cast<const bf16x8*>(Krs + KRSWZ(r32, cb)) : *reinterpret_cast<const bf16x8*>(Ks + KSWZ(r32, cb));
;         const bf16x8 b1 = rope ? *reinterpret_cast<const bf16x8*>(Krs + KRSWZ(32 + r32, cb)) : *reinterpret_cast<const bf16x8*>(Ks + KSWZ(32 + r32, cb));
;         if (s_ == 0) { n0 = __builtin_amdgcn_mfma_f32_32x32x16_bf16(b0, qr[0], cinit, 0, 0, 0); n1 = __builtin_amdgcn_mfma_f32_32x32x16_bf16(b1, qr[0], cinit, 0, 0, 0); }
;         else { n0 = __builtin_amdgcn_mfma_f32_32x32x16_bf16(b0, qr[s_], n0, 0, 0, 0); n1 = __builtin_amdgcn_mfma_f32_32x32x16_bf16(b1, qr[s_], n1, 0, 0, 0); }
;         if (s_ < 8) { p1[2 * s_] = __builtin_amdgcn_exp2f(p1[2 * s_]); p1[2 * s_ + 1] = __builtin_amdgcn_exp2f(p1[2 * s_ + 1]); ps += p1[2 * s_] + p1[2 * s_ + 1]; }
;         if (s_ == 4) PK4(p1, 0, pa2);
;         if (MLA && s_ == 8) { LFIN(); PK4(p1, 8, pa3); }
;         SBAR();
;     }
;     if (!MLA) { LFIN(); PK4(p1, 8, pa3); }
; }
; __device__ __forceinline__ int v_st(int k, int c) { const int kk = (k & ~0xC) | ((k & 4) << 1) | ((k & 8) >> 1); return ((kk >> 3) * 4 + (c >> 5)) * 512 + ((kk & 7) * 32 + (c & 31)) * 2; }
; __device__ __forceinline__ int v_rd_base(int lane) { return ((lane & 3) << 3) | (((lane >> 2) & 3) << 6) | (((lane >> 4) & 1) << 5) | (((lane >> 5) & 1) << 8); }
; template <int OFF> __device__ __forceinline__ s16x4 tr_read(int vb) {
;     s16x4 r; asm volatile("ds_read_b64_tr_b16 %0, %1 offset:%2" : "=&v"(r) : "v"(vb), "i"(OFF) : "memory"); return r;
; }
; template <int KS> __device__ __forceinline__ void pv_ks(f32x16* o, int vb, bf16x8 pa) {
;     const s16x4 l0 = tr_read<v_rd_off(0, KS, 0)>(vb), h0 = tr_read<v_rd_off(0, KS, 1)>(vb), l1 = tr_read<v_rd_off(1, KS, 0)>(vb), h1 = tr_read<v_rd_off(1, KS, 1)>(vb);
	v_mfma_f32_32x32x16_bf16 v[112:127], v[102:105], v[140:143], v[112:127]
	v_cvt_pk_bf16_f32 v102, v249, v186
	v_cvt_pk_bf16_f32 v103, v206, v207
	v_cvt_pk_bf16_f32 v104, v188, v189
	v_cvt_pk_bf16_f32 v105, v110, v111
	s_nop 0
	v_permlane32_swap_b32_e32 v102, v104
	v_mfma_f32_32x32x16_bf16 v[80:95], v[106:109], v[140:143], v[80:95]
	v_permlane32_swap_b32_e32 v103, v105
	v_add_u32_e32 v110, s10, v233
	v_add_u32_e32 v111, s10, v234
	ds_read_b128 v[106:109], v110 offset:49152
	ds_read_b128 v[228:231], v110 offset:53248
	ds_read_b128 v[188:191], v111 offset:49152
	ds_read_b128 v[236:239], v111 offset:53248
	v_add_u32_e32 v245, s10, v235
	s_waitcnt lgkmcnt(3)
	v_mfma_f32_32x32x16_bf16 v[112:127], v[106:109], v[136:139], v[112:127]
	s_waitcnt lgkmcnt(2)
	v_mfma_f32_32x32x16_bf16 v[80:95], v[228:231], v[136:139], v[80:95]
	ds_read_b128 v[106:109], v245 offset:49152
	ds_read_b128 v[228:231], v245 offset:53248
	s_waitcnt lgkmcnt(3)
	v_mfma_f32_32x32x16_bf16 v[112:127], v[188:191], v[132:135], v[112:127]
	s_waitcnt lgkmcnt(2)
	v_mfma_f32_32x32x16_bf16 v[80:95], v[236:239], v[132:135], v[80:95]
	s_waitcnt lgkmcnt(1)
	v_mfma_f32_32x32x16_bf16 v[112:127], v[106:109], v[128:131], v[112:127]
	s_waitcnt lgkmcnt(0)
	v_mfma_f32_32x32x16_bf16 v[80:95], v[228:231], v[128:131], v[80:95]
	v_add_u32_e32 v110, s15, v210
	ds_read_b64_tr_b16 v[106:107], v110 offset:0
	ds_read_b64_tr_b16 v[108:109], v110 offset:0x800
	ds_read_b64_tr_b16 v[188:189], v110 offset:0x200
	ds_read_b64_tr_b16 v[190:191], v110 offset:0xa00
	ds_read_b64_tr_b16 v[246:247], v110 offset:0x400
	ds_read_b64_tr_b16 v[248:249], v110 offset:0xc00
	ds_read_b64_tr_b16 v[206:207], v110 offset:0x600
	ds_read_b64_tr_b16 v[208:209], v110 offset:0xe00
	ds_read_b64_tr_b16 v[228:229], v110 offset:0x1000
	ds_read_b64_tr_b16 v[230:231], v110 offset:0x1800
	ds_read_b64_tr_b16 v[236:237], v110 offset:0x1200
	ds_read_b64_tr_b16 v[238:239], v110 offset:0x1a00
	v_max_f32_e32 v111, v113, v113
	v_max_f32_e32 v245, v112, v112
	v_max_f32_e32 v111, v245, v111
	v_max3_f32 v111, v111, v114, v115
	v_max3_f32 v111, v111, v116, v117
	v_max3_f32 v111, v111, v118, v119
	v_max3_f32 v111, v111, v120, v121
	v_max3_f32 v111, v111, v122, v123
	v_max3_f32 v111, v111, v124, v125
	v_max3_f32 v111, v111, v126, v127
	s_waitcnt lgkmcnt(4)
	v_mfma_f32_32x32x16_bf16 v[0:15], v[180:183], v[106:109], v[0:15]
	ds_read_b64_tr_b16 v[106:107], v110 offset:0x1400
	ds_read_b64_tr_b16 v[108:109], v110 offset:0x1c00
	v_max3_f32 v111, v111, v80, v81
	v_max3_f32 v111, v111, v82, v83
	v_mfma_f32_32x32x16_bf16 v[48:63], v[180:183], v[188:191], v[48:63]
	ds_read_b64_tr_b16 v[188:189], v110 offset:0x1600
	ds_read_b64_tr_b16 v[190:191], v110 offset:0x1e00
	v_max3_f32 v111, v111, v84, v85
	v_max3_f32 v111, v111, v86, v87
	v_mfma_f32_32x32x16_bf16 v[32:47], v[180:183], v[246:249], v[32:47]
	v_max3_f32 v111, v111, v88, v89
	v_max3_f32 v111, v111, v90, v91
	v_mfma_f32_32x32x16_bf16 v[16:31], v[180:183], v[206:209], v[16:31]
	ds_read_b64_tr_b16 v[246:247], v110 offset:0x2000
	ds_read_b64_tr_b16 v[248:249], v110 offset:0x2800
	ds_read_b64_tr_b16 v[206:207], v110 offset:0x2200
	ds_read_b64_tr_b16 v[208:209], v110 offset:0x2a00
	v_max3_f32 v111, v111, v92, v93
	v_max3_f32 v111, v111, v94, v95
	v_mov_b32_e32 v245, v111
	s_waitcnt lgkmcnt(4)
	v_mfma_f32_32x32x16_bf16 v[0:15], v[176:179], v[228:231], v[0:15]
	ds_read_b64_tr_b16 v[228:229], v110 offset:0x2400
	ds_read_b64_tr_b16 v[230:231], v110 offset:0x2c00
	v_permlane32_swap_b32_e32 v111, v245
	v_mfma_f32_32x32x16_bf16 v[48:63], v[176:179], v[236:239], v[48:63]
	ds_read_b64_tr_b16 v[236:237], v110 offset:0x2600
	ds_read_b64_tr_b16 v[238:239], v110 offset:0x2e00
	v_max_f32_e32 v245, v245, v245
	v_max_f32_e32 v111, v111, v111
	v_max_f32_e32 v111, v111, v245
	v_mfma_f32_32x32x16_bf16 v[32:47], v[176:179], v[106:109], v[32:47]
	v_cmp_ge_f32_e32 vcc, s90, v111
	s_cmp_eq_u64 vcc, exec
	v_mov_b32_e32 v243, 1.0
	v_mfma_f32_32x32x16_bf16 v[16:31], v[176:179], v[188:191], v[16:31]
	ds_read_b64_tr_b16 v[106:107], v110 offset:0x3000
	ds_read_b64_tr_b16 v[108:109], v110 offset:0x3800
	ds_read_b64_tr_b16 v[188:189], v110 offset:0x3200
	ds_read_b64_tr_b16 v[190:191], v110 offset:0x3a00
	s_cbranch_scc0 .LBB0_483

; #define SBAR() __builtin_amdgcn_sched_barrier(0)
; #define DMA_V(t, s) do { const bf16_t* vp_ = Vh + (long)(t) * KVBLK * ldk; \
;     __builtin_amdgcn_global_load_lds((const unsigned*)(vp_ + voff), (LAS unsigned*)(ldsl + OFF_V + (s) * SHM_V + widu * 1024), 16, 0, 0); \
;     __builtin_amdgcn_global_load_lds((const unsigned*)(vp_ + 32 * ldk + voff), (LAS unsigned*)(ldsl + OFF_V + (s) * SHM_V + 8192 + widu * 1024), 16, 0, 0); } while (0)
; #define WAITBAR_FULL() asm volatile("s_waitcnt vmcnt(0) lgkmcnt(0)\n\ts_barrier" ::: "memory")
; #define WAITBAR_G1() do { if constexpr (MLA) asm volatile("s_waitcnt vmcnt(5) lgkmcnt(0)\n\ts_barrier" ::: "memory"); else asm volatile("s_waitcnt vmcnt(4) lgkmcnt(0)\n\ts_barrier" ::: "memory"); } while (0)
; #define RESC(a) do { if (__any((a) < 1.f)) { if (hi == 0) al_l[r32] = (a); asm volatile("s_waitcnt lgkmcnt(0)" ::: "memory"); \
;     _Pragma("unroll") for (int d = 0; d < 4; ++d) _Pragma("unroll") for (int r = 0; r < 16; ++r) o[d][r] *= al_l[crow(r, hi)]; } } while (0)
; #define FIX(P0, P1, t) do { if constexpr (!MLA) swa_fix(P0, P1, bt, relq + (t) * KVBLK, hi); } while (0)
; #define ROT() do { sp = sc; sc = sn; sn = (sn == 2) ? 0 : sn + 1; } while (0)
; #define PSM(P0, P1, MN, AL, FIRST) do { if constexpr (MLA) partialSM_mla<FIRST>(P0, P1, m_reg, negm, AL); else partialSM<false>(P0, P1, m_reg, MN, AL); pack_p0(P0, pa0, pa1, ps0); } while (0)
; template <bool MLA, int ldq, int ldk, int ldo, bool GQA4 = false> ...
;     ...
;         if (j + 3 < NT) DMA_K(j + 3, sc); DMA_V(j + 2, sp);
;         ROT();
;         SBAR(); qkt_fin<MLA>(pA0, pA1, K_lds + sc * SHM_K, Kr_lds + sc * SHM_KR, qr, r32, hi, negm, pB1, alB, l_reg, ps0, pa2, pa3); FIX(pA0, pA1, j + 1); SBAR();
;         pv_d0(o, vb0 + sp * SHM_V, pa0, pa1, pa2, pa3); PSM(pA0, pA1, mnA, alA, false);
;         RESC(alA);
;         if (j + 3 < NT) { WAITBAR_G1(); } else { WAITBAR_FULL(); }
;         if (j + 4 < NT) DMA_K(j + 4, sc); if (j + 3 < NT) DMA_V(j + 3, sp);
;         ROT();
.LBB0_475:
	s_add_u32 s8, s84, 0x1ef40000
	s_addc_u32 s9, s85, 0
	s_add_i32 s10, s24, s19
	s_mov_b32 m0, s10
	s_nop 0
	global_load_lds_dwordx4 v196, s[8:9]
	s_add_u32 s8, s84, 0x1ef60000
	s_addc_u32 s9, s85, 0
	s_add_i32 m0, s10, 0x2000
	s_nop 0
	global_load_lds_dwordx4 v196, s[8:9]
	s_add_u32 s8, s84, 0x90a000
	s_addc_u32 s9, s85, 0
	s_add_i32 s10, s20, s25
	s_add_i32 m0, s10, 0xc000
	s_nop 0
	global_load_lds_dwordx4 v194, s[8:9]
.LBB0_476:
	s_add_i32 s8, s13, 1
	s_cmp_lg_u32 s13, 2
	s_cselect_b32 s24, s8, 0
	s_andn2_b64 vcc, exec, s[6:7]
	s_mov_b64 s[6:7], -1
	s_cbranch_vccnz .LBB0_478
	s_add_u32 s6, s84, 0x1ef00100
	s_addc_u32 s7, s85, 0
	s_add_i32 s8, s12, s15
	s_add_i32 s9, s8, 0x2000
	s_mov_b32 m0, s8
	s_nop 0
	global_load_lds_dwordx4 v198, s[6:7]
	s_add_u32 s6, s84, 0x1ef20100
	s_addc_u32 s7, s85, 0
	s_mov_b32 m0, s9
	s_nop 0
	global_load_lds_dwordx4 v198, s[6:7]
	s_add_i32 s6, s24, 1
	s_cmp_lg_u32 s24, 2
	s_cselect_b32 s8, s6, 0
	v_add_u32_e32 v194, 0x4000, v194
	v_add_u32_e32 v196, 0x80000, v196
	v_add_u32_e32 v198, 0x80000, v198
	s_add_i32 s14, s14, 2
	s_mov_b64 s[6:7], 0
